# 32x32x16 attention loop: S-chain MFMAs separated by PV MFMAs (S,PV,PV,S,PV,PV) per 16-key step
# speedup vs baseline: 1.0110x; 1.0110x over previous
.Lattn_nf_loop:
	s_and_b32 s10, s15, 1
	s_mul_i32 s6, s10, 0x8800
	v_add_u32_e32 v136, s6, v137
	v_add_u32_e32 v170, s6, v183
	s_sub_u32 s10, 0x8800, s6
	ds_read_b128 v[98:101], v136 offset:0
	ds_read_b128 v[102:105], v136 offset:32
	ds_read_b128 v[106:109], v136 offset:64
	ds_read_b128 v[110:113], v136 offset:96
	v_add_u32_e32 v171, s10, v126
	v_add_u32_e32 v173, s10, v127
	global_load_dwordx4 v[82:85], v124, s[64:65]
	global_load_dwordx4 v[86:89], v124, s[66:67]
	global_load_dwordx4 v[90:93], v124, s[68:69]
	global_load_dwordx4 v[94:97], v124, s[70:71]
	v_add_u32_e32 v124, s36, v124
	s_waitcnt lgkmcnt(3)
	v_mfma_f32_32x32x16_bf16 v[138:153], v[98:101], v[10:13], 0
	ds_read_b128 v[98:101], v136 offset:8704
	s_waitcnt lgkmcnt(3)
	v_mfma_f32_32x32x16_bf16 v[138:153], v[102:105], v[14:17], v[138:153]
	ds_read_b128 v[102:105], v136 offset:8736
	s_waitcnt lgkmcnt(3)
	v_mfma_f32_32x32x16_bf16 v[138:153], v[106:109], v[2:5], v[138:153]
	ds_read_b128 v[106:109], v136 offset:8768
	s_waitcnt lgkmcnt(3)
	v_mfma_f32_32x32x16_bf16 v[138:153], v[110:113], v[6:9], v[138:153]
	ds_read_b128 v[110:113], v136 offset:8800
	ds_read_b128 v[128:131], v170 offset:0
	ds_read_b128 v[184:187], v170 offset:8704
	ds_read_b128 v[188:191], v170 offset:17408
	ds_read_b128 v[192:195], v170 offset:26112
	s_waitcnt lgkmcnt(7)
	v_mfma_f32_32x32x16_bf16 v[154:169], v[98:101], v[10:13], 0
	ds_read_b128 v[98:101], v136 offset:17408
	s_nop 3
	v_exp_f32_e32 v138, v138
	v_exp_f32_e32 v139, v139
	v_exp_f32_e32 v140, v140
	v_exp_f32_e32 v141, v141
	v_exp_f32_e32 v142, v142
	v_exp_f32_e32 v143, v143
	s_waitcnt lgkmcnt(7)
	v_mfma_f32_32x32x16_bf16 v[154:169], v[102:105], v[14:17], v[154:169]
	ds_read_b128 v[102:105], v136 offset:17440
	v_exp_f32_e32 v144, v144
	v_exp_f32_e32 v145, v145
	v_add_f32_e32 v122, v138, v122
	v_add_f32_e32 v122, v139, v122
	v_add_f32_e32 v122, v140, v122
	v_add_f32_e32 v122, v141, v122
	v_add_f32_e32 v122, v142, v122
	v_add_f32_e32 v122, v143, v122
	v_add_f32_e32 v122, v144, v122
	v_add_f32_e32 v122, v145, v122
	v_cvt_pk_bf16_f32 v114, v138, v139
	v_cvt_pk_bf16_f32 v115, v140, v141
	v_cvt_pk_bf16_f32 v116, v142, v143
	v_cvt_pk_bf16_f32 v117, v144, v145
	ds_read_b128 v[196:199], v170 offset:32
	ds_read_b128 v[216:219], v170 offset:8736
	ds_read_b128 v[200:203], v170 offset:17440
	ds_read_b128 v[204:207], v170 offset:26144
	s_waitcnt lgkmcnt(11)
	v_mfma_f32_32x32x16_bf16 v[154:169], v[106:109], v[2:5], v[154:169]
	ds_read_b128 v[106:109], v136 offset:17472
	v_exp_f32_e32 v146, v146
	v_exp_f32_e32 v147, v147
	s_waitcnt lgkmcnt(10)
	v_mfma_f32_32x32x16_bf16 v[18:33], v[128:131], v[114:117], v[18:33]
	v_exp_f32_e32 v148, v148
	v_exp_f32_e32 v149, v149
	s_waitcnt lgkmcnt(9)
	v_mfma_f32_32x32x16_bf16 v[34:49], v[184:187], v[114:117], v[34:49]
	v_exp_f32_e32 v150, v150
	v_exp_f32_e32 v151, v151
	v_mfma_f32_32x32x16_bf16 v[154:169], v[110:113], v[6:9], v[154:169]
	ds_read_b128 v[110:113], v136 offset:17504
	v_exp_f32_e32 v152, v152
	v_exp_f32_e32 v153, v153
	s_waitcnt lgkmcnt(9)
	v_mfma_f32_32x32x16_bf16 v[50:65], v[188:191], v[114:117], v[50:65]
	v_add_f32_e32 v122, v146, v122
	v_add_f32_e32 v122, v147, v122
	v_add_f32_e32 v122, v148, v122
	v_add_f32_e32 v122, v149, v122
	s_waitcnt lgkmcnt(8)
	v_mfma_f32_32x32x16_bf16 v[66:81], v[192:195], v[114:117], v[66:81]
	v_add_f32_e32 v122, v150, v122
	v_add_f32_e32 v122, v151, v122
	v_add_f32_e32 v122, v152, v122
	v_add_f32_e32 v122, v153, v122
	v_cvt_pk_bf16_f32 v118, v146, v147
	v_cvt_pk_bf16_f32 v119, v148, v149
	v_cvt_pk_bf16_f32 v120, v150, v151
	v_cvt_pk_bf16_f32 v121, v152, v153
	ds_read_b128 v[128:131], v170 offset:64
	ds_read_b128 v[184:187], v170 offset:8768
	ds_read_b128 v[188:191], v170 offset:17472
	ds_read_b128 v[192:195], v170 offset:26176
	s_waitcnt lgkmcnt(11)
	v_mfma_f32_32x32x16_bf16 v[138:153], v[98:101], v[10:13], 0
	ds_read_b128 v[98:101], v136 offset:26112
	v_exp_f32_e32 v154, v154
	v_exp_f32_e32 v155, v155
	s_waitcnt lgkmcnt(10)
	v_mfma_f32_32x32x16_bf16 v[18:33], v[196:199], v[118:121], v[18:33]
	v_exp_f32_e32 v156, v156
	v_exp_f32_e32 v157, v157
	s_waitcnt lgkmcnt(9)
	v_mfma_f32_32x32x16_bf16 v[34:49], v[216:219], v[118:121], v[34:49]
	v_exp_f32_e32 v158, v158
	v_exp_f32_e32 v159, v159
	v_mfma_f32_32x32x16_bf16 v[138:153], v[102:105], v[14:17], v[138:153]
	ds_read_b128 v[102:105], v136 offset:26144
	v_exp_f32_e32 v160, v160
	v_exp_f32_e32 v161, v161
	s_waitcnt lgkmcnt(9)
	v_mfma_f32_32x32x16_bf16 v[50:65], v[200:203], v[118:121], v[50:65]
	v_add_f32_e32 v122, v154, v122
	v_add_f32_e32 v122, v155, v122
	v_add_f32_e32 v122, v156, v122
	v_add_f32_e32 v122, v157, v122
	s_waitcnt lgkmcnt(8)
	v_mfma_f32_32x32x16_bf16 v[66:81], v[204:207], v[118:121], v[66:81]
	v_add_f32_e32 v122, v158, v122
	v_add_f32_e32 v122, v159, v122
	v_add_f32_e32 v122, v160, v122
	v_add_f32_e32 v122, v161, v122
	v_cvt_pk_bf16_f32 v114, v154, v155
	v_cvt_pk_bf16_f32 v115, v156, v157
	v_cvt_pk_bf16_f32 v116, v158, v159
	v_cvt_pk_bf16_f32 v117, v160, v161
	ds_read_b128 v[196:199], v170 offset:96
	ds_read_b128 v[216:219], v170 offset:8800
	ds_read_b128 v[200:203], v170 offset:17504
	ds_read_b128 v[204:207], v170 offset:26208
	s_waitcnt lgkmcnt(11)
	v_mfma_f32_32x32x16_bf16 v[138:153], v[106:109], v[2:5], v[138:153]
	ds_read_b128 v[106:109], v136 offset:26176
	v_exp_f32_e32 v162, v162
	v_exp_f32_e32 v163, v163
	s_waitcnt lgkmcnt(10)
	v_mfma_f32_32x32x16_bf16 v[18:33], v[128:131], v[114:117], v[18:33]
	v_exp_f32_e32 v164, v164
	v_exp_f32_e32 v165, v165
	s_waitcnt lgkmcnt(9)
	v_mfma_f32_32x32x16_bf16 v[34:49], v[184:187], v[114:117], v[34:49]
	v_exp_f32_e32 v166, v166
	v_exp_f32_e32 v167, v167
	v_mfma_f32_32x32x16_bf16 v[138:153], v[110:113], v[6:9], v[138:153]
	ds_read_b128 v[110:113], v136 offset:26208
	v_exp_f32_e32 v168, v168
	v_exp_f32_e32 v169, v169
	s_waitcnt lgkmcnt(9)
	v_mfma_f32_32x32x16_bf16 v[50:65], v[188:191], v[114:117], v[50:65]
	v_add_f32_e32 v122, v162, v122
	v_add_f32_e32 v122, v163, v122
	v_add_f32_e32 v122, v164, v122
	v_add_f32_e32 v122, v165, v122
	s_waitcnt lgkmcnt(8)
	v_mfma_f32_32x32x16_bf16 v[66:81], v[192:195], v[114:117], v[66:81]
	v_add_f32_e32 v122, v166, v122
	v_add_f32_e32 v122, v167, v122
	v_add_f32_e32 v122, v168, v122
	v_add_f32_e32 v122, v169, v122
	v_cvt_pk_bf16_f32 v118, v162, v163
	v_cvt_pk_bf16_f32 v119, v164, v165
	v_cvt_pk_bf16_f32 v120, v166, v167
	v_cvt_pk_bf16_f32 v121, v168, v169
	ds_read_b128 v[128:131], v170 offset:128
	ds_read_b128 v[184:187], v170 offset:8832
	ds_read_b128 v[188:191], v170 offset:17536
	ds_read_b128 v[192:195], v170 offset:26240
	s_waitcnt lgkmcnt(11)
	v_mfma_f32_32x32x16_bf16 v[154:169], v[98:101], v[10:13], 0
	v_exp_f32_e32 v138, v138
	s_waitcnt lgkmcnt(9)
	v_mfma_f32_32x32x16_bf16 v[18:33], v[196:199], v[118:121], v[18:33]
	v_exp_f32_e32 v139, v139
	v_exp_f32_e32 v140, v140
	s_waitcnt lgkmcnt(8)
	v_mfma_f32_32x32x16_bf16 v[34:49], v[216:219], v[118:121], v[34:49]
	v_exp_f32_e32 v141, v141
	v_exp_f32_e32 v142, v142
	s_waitcnt vmcnt(3)
	ds_write_b128 v171, v[82:85] offset:0
	s_waitcnt vmcnt(2)
	ds_write_b128 v171, v[86:89] offset:8704
	s_waitcnt vmcnt(1)
	ds_write_b128 v171, v[90:93] offset:17408
	s_waitcnt vmcnt(0)
	ds_write_b128 v171, v[94:97] offset:26112
	v_exp_f32_e32 v143, v143
	v_mfma_f32_32x32x16_bf16 v[154:169], v[102:105], v[14:17], v[154:169]
	v_exp_f32_e32 v144, v144
	v_exp_f32_e32 v145, v145
	v_add_f32_e32 v122, v138, v122
	s_waitcnt lgkmcnt(11)
	v_mfma_f32_32x32x16_bf16 v[50:65], v[200:203], v[118:121], v[50:65]
	v_add_f32_e32 v122, v139, v122
	v_add_f32_e32 v122, v140, v122
	v_add_f32_e32 v122, v141, v122
	s_waitcnt lgkmcnt(10)
	v_mfma_f32_32x32x16_bf16 v[66:81], v[204:207], v[118:121], v[66:81]
	v_add_f32_e32 v122, v142, v122
	v_add_f32_e32 v122, v143, v122
	v_add_f32_e32 v122, v144, v122
	v_add_f32_e32 v122, v145, v122
	v_cvt_pk_bf16_f32 v114, v138, v139
	v_cvt_pk_bf16_f32 v115, v140, v141
	v_cvt_pk_bf16_f32 v116, v142, v143
	v_cvt_pk_bf16_f32 v117, v144, v145
	ds_read_b128 v[196:199], v170 offset:160
	ds_read_b128 v[216:219], v170 offset:8864
	ds_read_b128 v[200:203], v170 offset:17568
	ds_read_b128 v[204:207], v170 offset:26272
	s_waitcnt lgkmcnt(13)
	v_mfma_f32_32x32x16_bf16 v[154:169], v[106:109], v[2:5], v[154:169]
	v_exp_f32_e32 v146, v146
	s_waitcnt lgkmcnt(11)
	v_mfma_f32_32x32x16_bf16 v[18:33], v[128:131], v[114:117], v[18:33]
	v_exp_f32_e32 v147, v147
	v_exp_f32_e32 v148, v148
	s_waitcnt lgkmcnt(10)
	v_mfma_f32_32x32x16_bf16 v[34:49], v[184:187], v[114:117], v[34:49]
	v_exp_f32_e32 v149, v149
	v_exp_f32_e32 v150, v150
	global_load_dwordx4 v[82:85], v125, s[72:73]
	global_load_dwordx4 v[86:89], v125, s[74:75]
	global_load_dwordx4 v[90:93], v125, s[76:77]
	global_load_dwordx4 v[94:97], v125, s[78:79]
	v_add_u32_e32 v125, s38, v125
	v_exp_f32_e32 v151, v151
	v_mfma_f32_32x32x16_bf16 v[154:169], v[110:113], v[6:9], v[154:169]
	v_exp_f32_e32 v152, v152
	v_exp_f32_e32 v153, v153
	v_add_f32_e32 v122, v146, v122
	s_waitcnt lgkmcnt(9)
	v_mfma_f32_32x32x16_bf16 v[50:65], v[188:191], v[114:117], v[50:65]
	v_add_f32_e32 v122, v147, v122
	v_add_f32_e32 v122, v148, v122
	v_add_f32_e32 v122, v149, v122
	s_waitcnt lgkmcnt(8)
	v_mfma_f32_32x32x16_bf16 v[66:81], v[192:195], v[114:117], v[66:81]
	v_add_f32_e32 v122, v150, v122
	v_add_f32_e32 v122, v151, v122
	v_add_f32_e32 v122, v152, v122
	v_add_f32_e32 v122, v153, v122
	v_cvt_pk_bf16_f32 v118, v146, v147
	v_cvt_pk_bf16_f32 v119, v148, v149
	v_cvt_pk_bf16_f32 v120, v150, v151
	v_cvt_pk_bf16_f32 v121, v152, v153
	ds_read_b128 v[128:131], v170 offset:192
	ds_read_b128 v[184:187], v170 offset:8896
	ds_read_b128 v[188:191], v170 offset:17600
	ds_read_b128 v[192:195], v170 offset:26304
	s_waitcnt lgkmcnt(7)
	v_mfma_f32_32x32x16_bf16 v[18:33], v[196:199], v[118:121], v[18:33]
	v_exp_f32_e32 v154, v154
	v_exp_f32_e32 v155, v155
	v_exp_f32_e32 v156, v156
	s_waitcnt lgkmcnt(6)
	v_mfma_f32_32x32x16_bf16 v[34:49], v[216:219], v[118:121], v[34:49]
	v_exp_f32_e32 v157, v157
	v_exp_f32_e32 v158, v158
	v_exp_f32_e32 v159, v159
	s_waitcnt lgkmcnt(5)
	v_mfma_f32_32x32x16_bf16 v[50:65], v[200:203], v[118:121], v[50:65]
	v_exp_f32_e32 v160, v160
	v_exp_f32_e32 v161, v161
	v_add_f32_e32 v122, v154, v122
	v_add_f32_e32 v122, v155, v122
	s_waitcnt lgkmcnt(4)
	v_mfma_f32_32x32x16_bf16 v[66:81], v[204:207], v[118:121], v[66:81]
	v_add_f32_e32 v122, v156, v122
	v_add_f32_e32 v122, v157, v122
	v_add_f32_e32 v122, v158, v122
	v_add_f32_e32 v122, v159, v122
	v_add_f32_e32 v122, v160, v122
	v_add_f32_e32 v122, v161, v122
	v_cvt_pk_bf16_f32 v114, v154, v155
	v_cvt_pk_bf16_f32 v115, v156, v157
	v_cvt_pk_bf16_f32 v116, v158, v159
	v_cvt_pk_bf16_f32 v117, v160, v161
	ds_read_b128 v[196:199], v170 offset:224
	ds_read_b128 v[216:219], v170 offset:8928
	ds_read_b128 v[200:203], v170 offset:17632
	ds_read_b128 v[204:207], v170 offset:26336
	s_waitcnt lgkmcnt(7)
	v_mfma_f32_32x32x16_bf16 v[18:33], v[128:131], v[114:117], v[18:33]
	v_exp_f32_e32 v162, v162
	v_exp_f32_e32 v163, v163
	v_exp_f32_e32 v164, v164
	s_waitcnt lgkmcnt(6)
	v_mfma_f32_32x32x16_bf16 v[34:49], v[184:187], v[114:117], v[34:49]
	v_exp_f32_e32 v165, v165
	v_exp_f32_e32 v166, v166
	v_exp_f32_e32 v167, v167
	s_waitcnt lgkmcnt(5)
	v_mfma_f32_32x32x16_bf16 v[50:65], v[188:191], v[114:117], v[50:65]
	v_exp_f32_e32 v168, v168
	v_exp_f32_e32 v169, v169
	v_add_f32_e32 v122, v162, v122
	v_add_f32_e32 v122, v163, v122
	s_waitcnt lgkmcnt(4)
	v_mfma_f32_32x32x16_bf16 v[66:81], v[192:195], v[114:117], v[66:81]
	v_add_f32_e32 v122, v164, v122
	v_add_f32_e32 v122, v165, v122
	v_add_f32_e32 v122, v166, v122
	v_add_f32_e32 v122, v167, v122
	v_add_f32_e32 v122, v168, v122
	v_add_f32_e32 v122, v169, v122
	v_cvt_pk_bf16_f32 v118, v162, v163
	v_cvt_pk_bf16_f32 v119, v164, v165
	v_cvt_pk_bf16_f32 v120, v166, v167
	v_cvt_pk_bf16_f32 v121, v168, v169
	s_waitcnt lgkmcnt(3)
	s_nop 0
	v_mfma_f32_32x32x16_bf16 v[18:33], v[196:199], v[118:121], v[18:33]
	s_waitcnt lgkmcnt(2)
	v_mfma_f32_32x32x16_bf16 v[34:49], v[216:219], v[118:121], v[34:49]
	s_waitcnt vmcnt(3)
	ds_write_b128 v173, v[82:85] offset:0
	s_waitcnt vmcnt(2)
	ds_write_b128 v173, v[86:89] offset:8704
	s_waitcnt vmcnt(1)
	ds_write_b128 v173, v[90:93] offset:17408
	s_waitcnt vmcnt(0)
	ds_write_b128 v173, v[94:97] offset:26112
	s_waitcnt lgkmcnt(5)
	v_mfma_f32_32x32x16_bf16 v[50:65], v[200:203], v[118:121], v[50:65]
	s_waitcnt lgkmcnt(4)
	v_mfma_f32_32x32x16_bf16 v[66:81], v[204:207], v[118:121], v[66:81]
	s_waitcnt lgkmcnt(0)
	s_barrier
	s_add_i32 s15, s15, 1
	s_cmp_eq_u32 s15, 34
	s_cbranch_scc0 .Lattn_nf_loop
	v_readlane_b32 s64, v175, 0
	v_readlane_b32 s65, v175, 1
	v_readlane_b32 s66, v175, 2
	v_readlane_b32 s67, v175, 3
	v_readlane_b32 s68, v175, 4
	v_readlane_b32 s69, v175, 5
	v_readlane_b32 s70, v175, 6
	v_readlane_b32 s71, v175, 7
	v_readlane_b32 s72, v175, 8
	v_readlane_b32 s73, v175, 9
	v_readlane_b32 s74, v175, 10
	v_readlane_b32 s75, v175, 11
	v_readlane_b32 s76, v175, 12
	v_readlane_b32 s77, v175, 13
	v_readlane_b32 s78, v175, 14
	v_readlane_b32 s79, v175, 15
	s_nop 4
	v_add_f32_e32 v186, v132, v134
	v_add_f32_e32 v184, v133, v135
	ds_bpermute_b32 v187, v172, v186
	ds_bpermute_b32 v185, v172, v184
	s_mov_b32 s10, 0x3fb8aa3b
	s_mov_b32 s11, 0xc2ce8ed0
	s_mov_b32 s6, 0x42b17218
	v_cmp_eq_u32_e64 s[40:41], 0, v179
	s_lshl_b32 s30, s14, 1
	v_lshlrev_b32_e32 v196, 3, v178
	v_mov_b32_e32 v197, 0
	v_lshlrev_b32_e32 v198, 4, v179
	v_or3_b32 v198, v198, v177, v180
	v_ashrrev_i32_e32 v199, 31, v198
	v_lshlrev_b64 v[198:199], 11, v[198:199]
	s_mov_b64 s[100:101], 0x18a10000
	v_lshl_add_u64 v[198:199], s[42:43], 0, v[198:199]
	v_lshl_add_u64 v[198:199], v[198:199], 0, s[30:31]
	v_lshl_add_u64 v[198:199], v[198:199], 0, v[196:197]
	v_lshl_add_u64 v[198:199], v[198:199], 0, s[100:101]
	global_load_dwordx2 v[146:147], v[198:199], off
	global_load_dwordx2 v[148:149], v[198:199], off offset:32
	global_load_dwordx2 v[150:151], v[198:199], off offset:64
	global_load_dwordx2 v[152:153], v[198:199], off offset:96
	global_load_dwordx2 v[188:189], v[198:199], off offset:128
	global_load_dwordx2 v[190:191], v[198:199], off offset:160
	global_load_dwordx2 v[192:193], v[198:199], off offset:192
	global_load_dwordx2 v[194:195], v[198:199], off offset:224
	s_mov_b64 s[100:101], exec
	s_and_b64 exec, exec, s[4:5]
	s_cbranch_execz .Lpop_skip
	v_readlane_b32 s14, v255, 22
	v_readlane_b32 s15, v255, 23
	v_mov_b32_e32 v224, 1
	s_nop 4
	global_atomic_add v224, v0, v224, s[14:15] sc0
